# multi-head norm phase: norm-weight vector kept in registers instead of re-loaded behind each row's store; row waits leave the youngest store in flight (on top of v40)
# baseline (speedup 1.0000x reference)
; __device__ __forceinline__ unsigned pk2(float lo, float hi) { unsigned r; asm("v_cvt_pk_bf16_f32 %0, %1, %2" : "=v"(r) : "v"(lo), "v"(hi)); return r; }
; __device__ __forceinline__ void phase_mlnorm(const Params& p) {
;     ...
;     for (int w0 = blockIdx.x * NWAVES + wave; w0 < T * 4; w0 += 4 * NW) {
;         u32x2 a[4], b[4]; unsigned o[4];
; #pragma unroll
;         for (int u = 0; u < 4; ++u) { const int wi = min(w0 + u * NW, T * 4 - 1); const size_t off = (size_t)wi * 256 + lane * 4;
;             a[u] = __builtin_nontemporal_load((const u32x2*)(H0 + off)); b[u] = __builtin_nontemporal_load((const u32x2*)(H1 + off)); o[u] = __builtin_nontemporal_load((const unsigned*)(mlo + off)); }
; #pragma unroll
;         for (int u = 0; u < 4; ++u) { const int wi = w0 + u * NW; if (wi >= T * 4) continue; const size_t off = (size_t)wi * 256 + lane * 4;
;             float v[4] = {bflo(a[u].x) + bflo(b[u].x), bfhi(a[u].x) + bfhi(b[u].x), bflo(a[u].y) + bflo(b[u].y), bfhi(a[u].y) + bfhi(b[u].y)};
;             const float mu = wave_sum((v[0] + v[1]) + (v[2] + v[3])) * (1.0f / 256.0f);
;             float q = 0.f;
; #pragma unroll
;             for (int i = 0; i < 4; ++i) { v[i] -= mu; q += v[i] * v[i]; }
;             const float rstd = 1.0f / sqrtf(wave_sum(q) * (1.0f / 256.0f) + LN_EPS);
;             const f32x4 nwv = *(const f32x4*)(nw + (wi & 3) * 256 + lane * 4);
;             const float og[4] = {(float)(o[u] & 0xffu) * (1.0f / 255.0f), (float)((o[u] >> 8) & 0xffu) * (1.0f / 255.0f), (float)((o[u] >> 16) & 0xffu) * (1.0f / 255.0f), (float)(o[u] >> 24) * (1.0f / 255.0f)};
;             u32x2 wv; wv.x = pk2(v[0] * rstd * nwv[0] * og[0], v[1] * rstd * nwv[1] * og[1]); wv.y = pk2(v[2] * rstd * nwv[2] * og[2], v[3] * rstd * nwv[3] * og[3]);
;             *(u32x2*)(yml + off) = wv; }
.LBB0_524:
	v_ashrrev_i32_e32 v23, 31, v22
	v_lshlrev_b64 v[12:13], 8, v[22:23]
	v_or_b32_e32 v12, v12, v0
	s_waitcnt vmcnt(3)
	v_lshlrev_b64 v[10:11], 1, v[12:13]
	v_lshl_add_u64 v[14:15], s[8:9], 0, v[10:11]
	v_lshl_add_u64 v[10:11], s[6:7], 0, v[10:11]
	global_load_dwordx2 v[16:17], v[10:11], off nt
	global_load_dwordx2 v[18:19], v[14:15], off nt
	v_add_u32_e32 v10, s22, v22
	v_min_i32_e32 v14, 0x1ffff, v10
	v_and_b32_e32 v2, 0x300, v37
	v_ashrrev_i32_e32 v15, 31, v14
	v_lshlrev_b32_e32 v2, 2, v2
	v_lshlrev_b64 v[24:25], 8, v[14:15]
	v_lshl_add_u64 v[14:15], v[4:5], 0, v[2:3]
	global_load_dwordx4 v[40:43], v[14:15], off
	v_or_b32_e32 v24, v24, v0
	v_lshl_add_u64 v[12:13], s[10:11], 0, v[12:13]
	s_waitcnt vmcnt(2)
	v_lshlrev_b32_e32 v20, 16, v16
	s_waitcnt vmcnt(1)
	v_lshlrev_b32_e32 v26, 16, v18
	v_and_b32_e32 v16, 0xffff0000, v16
	v_and_b32_e32 v18, 0xffff0000, v18
	v_lshlrev_b32_e32 v21, 16, v17
	v_lshlrev_b32_e32 v27, 16, v19
	v_and_b32_e32 v17, 0xffff0000, v17
	v_and_b32_e32 v19, 0xffff0000, v19
	v_pk_add_f32 v[44:45], v[26:27], v[20:21]
	v_pk_add_f32 v[46:47], v[18:19], v[16:17]
	v_add_u32_e32 v20, s21, v22
	v_pk_add_f32 v[16:17], v[44:45], v[46:47]
	v_min_i32_e32 v18, 0x1ffff, v20
	v_add_f32_e32 v9, v16, v17
	ds_bpermute_b32 v11, v1, v9
	v_lshl_add_u64 v[16:17], s[10:11], 0, v[24:25]
	global_load_dword v2, v[16:17], off nt
	global_load_dword v60, v[12:13], off nt
	v_add_u32_e32 v12, s19, v22
	v_min_i32_e32 v16, 0x1ffff, v12
	s_waitcnt lgkmcnt(0)
	v_add_f32_e32 v9, v9, v11
	ds_bpermute_b32 v11, v32, v9
	v_ashrrev_i32_e32 v17, 31, v16
	v_ashrrev_i32_e32 v19, 31, v18
	v_lshlrev_b64 v[16:17], 8, v[16:17]
	v_lshlrev_b64 v[18:19], 8, v[18:19]
	s_waitcnt lgkmcnt(0)
	v_add_f32_e32 v9, v9, v11
	ds_bpermute_b32 v11, v33, v9
	v_or_b32_e32 v16, v16, v0
	v_or_b32_e32 v18, v18, v0
	v_lshlrev_b64 v[26:27], 1, v[16:17]
	v_lshlrev_b64 v[28:29], 1, v[18:19]
	s_waitcnt lgkmcnt(0)
	v_add_f32_e32 v9, v9, v11
	ds_bpermute_b32 v11, v34, v9
	v_lshl_add_u64 v[16:17], s[10:11], 0, v[16:17]
	v_lshl_add_u64 v[48:49], s[10:11], 0, v[18:19]
	v_lshlrev_b64 v[18:19], 1, v[24:25]
	v_lshl_add_u64 v[50:51], s[6:7], 0, v[26:27]
	s_waitcnt lgkmcnt(0)
	v_add_f32_e32 v9, v9, v11
	ds_bpermute_b32 v11, v35, v9
	v_lshl_add_u64 v[26:27], s[8:9], 0, v[26:27]
	v_lshl_add_u64 v[54:55], s[8:9], 0, v[28:29]
	v_lshl_add_u64 v[52:53], s[6:7], 0, v[28:29]
	v_lshl_add_u64 v[56:57], s[6:7], 0, v[18:19]
	s_waitcnt lgkmcnt(0)
	v_add_f32_e32 v9, v9, v11
	ds_bpermute_b32 v11, v36, v9
	v_lshl_add_u64 v[58:59], s[8:9], 0, v[18:19]
	global_load_dwordx2 v[28:29], v[50:51], off nt
	global_load_dwordx2 v[30:31], v[26:27], off nt
	global_load_dword v21, v[16:17], off nt
	global_load_dwordx2 v[24:25], v[52:53], off nt
	s_waitcnt vmcnt(6)
	v_mov_b32_e32 v64, v40
	v_mov_b32_e32 v65, v41
	v_mov_b32_e32 v66, v42
	v_mov_b32_e32 v67, v43
	v_mov_b32_e32 v51, v42
	v_lshlrev_b64 v[22:23], 9, v[22:23]
	s_waitcnt lgkmcnt(0)
	v_add_f32_e32 v9, v9, v11
	v_fmamk_f32 v13, v9, 0xbb800000, v44
	v_fmamk_f32 v44, v9, 0xbb800000, v46
	v_fmac_f32_e32 v45, 0xbb800000, v9
	v_fmac_f32_e32 v47, 0xbb800000, v9
	v_mul_f32_e32 v9, v44, v44
	v_fmac_f32_e32 v9, v13, v13
	v_fmac_f32_e32 v9, v45, v45
	v_fmac_f32_e32 v9, v47, v47
	ds_bpermute_b32 v11, v1, v9
	v_lshl_add_u64 v[22:23], v[6:7], 0, v[22:23]
	s_waitcnt lgkmcnt(0)
	v_add_f32_e32 v9, v9, v11
	global_load_dwordx2 v[26:27], v[54:55], off nt
	global_load_dword v11, v[48:49], off nt
	global_load_dwordx2 v[16:17], v[56:57], off nt
	global_load_dwordx2 v[18:19], v[58:59], off nt
	ds_bpermute_b32 v46, v32, v9
	v_mov_b32_e32 v49, v40
	s_waitcnt lgkmcnt(0)
	v_add_f32_e32 v9, v9, v46
	ds_bpermute_b32 v46, v33, v9
	s_waitcnt lgkmcnt(0)
	v_add_f32_e32 v9, v9, v46
	ds_bpermute_b32 v46, v34, v9
	s_waitcnt lgkmcnt(0)
	v_add_f32_e32 v9, v9, v46
	ds_bpermute_b32 v46, v35, v9
	s_waitcnt lgkmcnt(0)
	v_add_f32_e32 v9, v9, v46
	ds_bpermute_b32 v46, v36, v9
	s_waitcnt lgkmcnt(0)
	v_add_f32_e32 v9, v9, v46
	v_fmamk_f32 v9, v9, 0x3b800000, v38
	v_mul_f32_e32 v40, 0x4f800000, v9
	v_cmp_gt_f32_e32 vcc, s24, v9
	s_waitcnt vmcnt(8)
	v_cvt_f32_ubyte0_e32 v48, v60
	v_cvt_f32_ubyte2_e32 v50, v60
	v_cndmask_b32_e32 v9, v9, v40, vcc
	v_sqrt_f32_e32 v42, v9
	v_cvt_f32_ubyte1_e32 v40, v60
	v_add_u32_e32 v46, -1, v42
	v_add_u32_e32 v52, 1, v42
	v_fma_f32 v53, -v46, v42, v9
	v_fma_f32 v54, -v52, v42, v9
	v_cmp_ge_f32_e64 s[0:1], 0, v53
	s_nop 1
	v_cndmask_b32_e64 v42, v42, v46, s[0:1]
	v_cmp_lt_f32_e64 s[0:1], 0, v54
	s_nop 1
	v_cndmask_b32_e64 v42, v42, v52, s[0:1]
	v_mul_f32_e32 v46, 0x37800000, v42
	v_cndmask_b32_e32 v42, v42, v46, vcc
	v_cmp_class_f32_e32 vcc, v9, v39
	s_nop 1
	v_cndmask_b32_e32 v9, v42, v9, vcc
	v_div_scale_f32 v46, s[0:1], v9, v9, 1.0
	v_rcp_f32_e32 v52, v46
	v_div_scale_f32 v53, vcc, 1.0, v9, 1.0
	v_cvt_f32_ubyte3_e32 v42, v60
	v_fma_f32 v54, -v46, v52, 1.0
	v_fmac_f32_e32 v52, v54, v52
	v_mul_f32_e32 v54, v53, v52
	v_fma_f32 v55, -v46, v54, v53
	v_fmac_f32_e32 v54, v55, v52
	v_fma_f32 v46, -v46, v54, v53
	v_div_fmas_f32 v46, v46, v52, v54
	v_div_fixup_f32 v46, v46, v9, 1.0
	v_mul_f32_e32 v9, v13, v46
	v_pk_mul_f32 v[48:49], v[48:49], v[8:9]
	v_mul_f32_e32 v9, v44, v46
	v_pk_mul_f32 v[40:41], v[40:41], v[8:9]
	v_mul_f32_e32 v9, v45, v46
	v_mul_f32_e32 v13, v48, v49
	v_mul_f32_e32 v44, v40, v41
	v_pk_mul_f32 v[40:41], v[50:51], v[8:9]
	v_mul_f32_e32 v9, v47, v46
	v_cvt_pk_bf16_f32 v44, v13, v44
	v_mul_f32_e32 v13, v40, v41
	v_pk_mul_f32 v[40:41], v[42:43], v[8:9]
	v_cmp_gt_i32_e32 vcc, s18, v12
	v_mul_f32_e32 v9, v40, v41
	v_cvt_pk_bf16_f32 v45, v13, v9
	global_store_dwordx2 v[22:23], v[44:45], off
	s_and_saveexec_b64 s[14:15], vcc
	s_cbranch_execz .LBB0_527
; __device__ __forceinline__ unsigned pk2(float lo, float hi) { unsigned r; asm("v_cvt_pk_bf16_f32 %0, %1, %2" : "=v"(r) : "v"(lo), "v"(hi)); return r; }
; __device__ __forceinline__ void phase_mlnorm(const Params& p) {
;     ...
;         for (int u = 0; u < 4; ++u) { const int wi = w0 + u * NW; if (wi >= T * 4) continue; const size_t off = (size_t)wi * 256 + lane * 4;
;             float v[4] = {bflo(a[u].x) + bflo(b[u].x), bfhi(a[u].x) + bfhi(b[u].x), bflo(a[u].y) + bflo(b[u].y), bfhi(a[u].y) + bfhi(b[u].y)};
;             const float mu = wave_sum((v[0] + v[1]) + (v[2] + v[3])) * (1.0f / 256.0f);
;             float q = 0.f;
; #pragma unroll
;             for (int i = 0; i < 4; ++i) { v[i] -= mu; q += v[i] * v[i]; }
;             const float rstd = 1.0f / sqrtf(wave_sum(q) * (1.0f / 256.0f) + LN_EPS);
;             const f32x4 nwv = *(const f32x4*)(nw + (wi & 3) * 256 + lane * 4);
;             const float og[4] = {(float)(o[u] & 0xffu) * (1.0f / 255.0f), (float)((o[u] >> 8) & 0xffu) * (1.0f / 255.0f), (float)((o[u] >> 16) & 0xffu) * (1.0f / 255.0f), (float)(o[u] >> 24) * (1.0f / 255.0f)};
;             u32x2 wv; wv.x = pk2(v[0] * rstd * nwv[0] * og[0], v[1] * rstd * nwv[1] * og[1]); wv.y = pk2(v[2] * rstd * nwv[2] * og[2], v[3] * rstd * nwv[3] * og[3]);
;             *(u32x2*)(yml + off) = wv; }
	s_waitcnt vmcnt(7)
	v_lshlrev_b32_e32 v22, 16, v30
	v_lshlrev_b32_e32 v40, 16, v28
	v_and_b32_e32 v30, 0xffff0000, v30
	v_and_b32_e32 v28, 0xffff0000, v28
	v_lshlrev_b32_e32 v23, 16, v31
	v_lshlrev_b32_e32 v41, 16, v29
	v_and_b32_e32 v31, 0xffff0000, v31
	v_and_b32_e32 v29, 0xffff0000, v29
	v_pk_add_f32 v[22:23], v[40:41], v[22:23]
	v_pk_add_f32 v[40:41], v[28:29], v[30:31]
	s_waitcnt vmcnt(6)
	v_cvt_f32_ubyte0_e32 v42, v21
	v_pk_add_f32 v[28:29], v[22:23], v[40:41]
	v_cvt_f32_ubyte1_e32 v44, v21
	v_add_f32_e32 v9, v28, v29
	ds_bpermute_b32 v13, v1, v9
	v_mov_b32_e32 v28, v64
	v_mov_b32_e32 v29, v65
	v_mov_b32_e32 v30, v66
	v_mov_b32_e32 v31, v67
	v_cvt_f32_ubyte2_e32 v46, v21
	v_cvt_f32_ubyte3_e32 v48, v21
	s_waitcnt lgkmcnt(0)
	v_add_f32_e32 v9, v9, v13
	ds_bpermute_b32 v13, v32, v9
	s_waitcnt lgkmcnt(0)
	v_add_f32_e32 v9, v9, v13
	ds_bpermute_b32 v13, v33, v9
	s_waitcnt lgkmcnt(0)
	v_add_f32_e32 v9, v9, v13
	ds_bpermute_b32 v13, v34, v9
	s_waitcnt lgkmcnt(0)
	v_add_f32_e32 v9, v9, v13
	ds_bpermute_b32 v13, v35, v9
	s_waitcnt lgkmcnt(0)
	v_add_f32_e32 v9, v9, v13
	ds_bpermute_b32 v13, v36, v9
	s_waitcnt lgkmcnt(0)
	v_add_f32_e32 v9, v9, v13
	v_fmamk_f32 v40, v9, 0xbb800000, v40
	v_fmamk_f32 v22, v9, 0xbb800000, v22
	v_fmac_f32_e32 v23, 0xbb800000, v9
	v_fmac_f32_e32 v41, 0xbb800000, v9
	v_mul_f32_e32 v9, v40, v40
	v_fmac_f32_e32 v9, v22, v22
	v_fmac_f32_e32 v9, v23, v23
	v_fmac_f32_e32 v9, v41, v41
	ds_bpermute_b32 v13, v1, v9
	s_waitcnt lgkmcnt(0)
	v_add_f32_e32 v9, v9, v13
	ds_bpermute_b32 v13, v32, v9
	s_waitcnt lgkmcnt(0)
	v_add_f32_e32 v9, v9, v13
	ds_bpermute_b32 v13, v33, v9
	s_waitcnt lgkmcnt(0)
	v_add_f32_e32 v9, v9, v13
	ds_bpermute_b32 v13, v34, v9
	s_waitcnt lgkmcnt(0)
	v_add_f32_e32 v9, v9, v13
	ds_bpermute_b32 v43, v35, v9
	v_ashrrev_i32_e32 v13, 31, v12
	v_lshlrev_b64 v[50:51], 9, v[12:13]
	s_waitcnt lgkmcnt(0)
	v_add_f32_e32 v9, v9, v43
	ds_bpermute_b32 v43, v36, v9
	s_waitcnt lgkmcnt(0)
	v_add_f32_e32 v9, v9, v43
	v_fmamk_f32 v9, v9, 0x3b800000, v38
	v_mul_f32_e32 v13, 0x4f800000, v9
	v_cmp_gt_f32_e32 vcc, s24, v9
	s_waitcnt vmcnt(1)
	v_mov_b32_e32 v43, v28
	v_mov_b32_e32 v45, v29
	v_cndmask_b32_e32 v9, v9, v13, vcc
	v_sqrt_f32_e32 v13, v9
	v_mov_b32_e32 v47, v30
	v_mov_b32_e32 v49, v31
	v_add_u32_e32 v21, -1, v13
	v_add_u32_e32 v28, 1, v13
	v_fma_f32 v29, -v21, v13, v9
	v_fma_f32 v30, -v28, v13, v9
	v_cmp_ge_f32_e64 s[0:1], 0, v29
	s_nop 1
	v_cndmask_b32_e64 v13, v13, v21, s[0:1]
	v_cmp_lt_f32_e64 s[0:1], 0, v30
	s_nop 1
	v_cndmask_b32_e64 v13, v13, v28, s[0:1]
	v_mul_f32_e32 v21, 0x37800000, v13
	v_cndmask_b32_e32 v13, v13, v21, vcc
	v_cmp_class_f32_e32 vcc, v9, v39
	s_nop 1
	v_cndmask_b32_e32 v9, v13, v9, vcc
	v_div_scale_f32 v13, s[0:1], v9, v9, 1.0
	v_rcp_f32_e32 v21, v13
	v_div_scale_f32 v28, vcc, 1.0, v9, 1.0
	v_fma_f32 v29, -v13, v21, 1.0
	v_fmac_f32_e32 v21, v29, v21
	v_mul_f32_e32 v29, v28, v21
	v_fma_f32 v30, -v13, v29, v28
	v_fmac_f32_e32 v29, v30, v21
	v_fma_f32 v13, -v13, v29, v28
	v_div_fmas_f32 v13, v13, v21, v29
	v_div_fixup_f32 v13, v13, v9, 1.0
	v_mul_f32_e32 v9, v22, v13
	v_pk_mul_f32 v[28:29], v[42:43], v[8:9]
	v_mul_f32_e32 v9, v40, v13
	v_mul_f32_e32 v21, v28, v29
	v_pk_mul_f32 v[28:29], v[44:45], v[8:9]
	v_mul_f32_e32 v9, v23, v13
	v_pk_mul_f32 v[22:23], v[46:47], v[8:9]
	v_mul_f32_e32 v9, v41, v13
	v_mul_f32_e32 v13, v22, v23
	v_pk_mul_f32 v[22:23], v[48:49], v[8:9]
	v_mul_f32_e32 v28, v28, v29
	v_mul_f32_e32 v9, v22, v23
	v_lshl_add_u64 v[22:23], v[6:7], 0, v[50:51]
	v_cvt_pk_bf16_f32 v28, v21, v28
	v_cvt_pk_bf16_f32 v29, v13, v9
	global_store_dwordx2 v[22:23], v[28:29], off
	s_or_b64 exec, exec, s[14:15]
	v_cmp_gt_i32_e32 vcc, s18, v20
	s_and_saveexec_b64 s[14:15], vcc
	s_cbranch_execnz .LBB0_528

; __device__ __forceinline__ unsigned pk2(float lo, float hi) { unsigned r; asm("v_cvt_pk_bf16_f32 %0, %1, %2" : "=v"(r) : "v"(lo), "v"(hi)); return r; }
; __device__ __forceinline__ void phase_mlnorm(const Params& p) {
;     ...
;         for (int u = 0; u < 4; ++u) { const int wi = w0 + u * NW; if (wi >= T * 4) continue; const size_t off = (size_t)wi * 256 + lane * 4;
;             float v[4] = {bflo(a[u].x) + bflo(b[u].x), bfhi(a[u].x) + bfhi(b[u].x), bflo(a[u].y) + bflo(b[u].y), bfhi(a[u].y) + bfhi(b[u].y)};
;             const float mu = wave_sum((v[0] + v[1]) + (v[2] + v[3])) * (1.0f / 256.0f);
;             float q = 0.f;
; #pragma unroll
;             for (int i = 0; i < 4; ++i) { v[i] -= mu; q += v[i] * v[i]; }
;             const float rstd = 1.0f / sqrtf(wave_sum(q) * (1.0f / 256.0f) + LN_EPS);
;             const f32x4 nwv = *(const f32x4*)(nw + (wi & 3) * 256 + lane * 4);
;             const float og[4] = {(float)(o[u] & 0xffu) * (1.0f / 255.0f), (float)((o[u] >> 8) & 0xffu) * (1.0f / 255.0f), (float)((o[u] >> 16) & 0xffu) * (1.0f / 255.0f), (float)(o[u] >> 24) * (1.0f / 255.0f)};
;             u32x2 wv; wv.x = pk2(v[0] * rstd * nwv[0] * og[0], v[1] * rstd * nwv[1] * og[1]); wv.y = pk2(v[2] * rstd * nwv[2] * og[2], v[3] * rstd * nwv[3] * og[3]);
;             *(u32x2*)(yml + off) = wv; }
.LBB0_528:
	s_waitcnt vmcnt(4)
	v_lshlrev_b32_e32 v22, 16, v26
	v_lshlrev_b32_e32 v28, 16, v24
	v_and_b32_e32 v26, 0xffff0000, v26
	v_and_b32_e32 v24, 0xffff0000, v24
	v_lshlrev_b32_e32 v23, 16, v27
	v_lshlrev_b32_e32 v29, 16, v25
	v_and_b32_e32 v27, 0xffff0000, v27
	v_and_b32_e32 v25, 0xffff0000, v25
	v_pk_add_f32 v[28:29], v[28:29], v[22:23]
	v_pk_add_f32 v[26:27], v[24:25], v[26:27]
	s_waitcnt vmcnt(3)
	v_cvt_f32_ubyte0_e32 v30, v11
	v_pk_add_f32 v[22:23], v[28:29], v[26:27]
	v_cvt_f32_ubyte1_e32 v40, v11
	v_add_f32_e32 v9, v22, v23
	ds_bpermute_b32 v13, v1, v9
	v_mov_b32_e32 v22, v64
	v_mov_b32_e32 v23, v65
	v_mov_b32_e32 v24, v66
	v_mov_b32_e32 v25, v67
	v_cvt_f32_ubyte2_e32 v42, v11
	v_cvt_f32_ubyte3_e32 v44, v11
	s_waitcnt lgkmcnt(0)
	v_add_f32_e32 v9, v9, v13
	ds_bpermute_b32 v13, v32, v9
	s_waitcnt lgkmcnt(0)
	v_add_f32_e32 v9, v9, v13
	ds_bpermute_b32 v13, v33, v9
	s_waitcnt lgkmcnt(0)
	v_add_f32_e32 v9, v9, v13
	ds_bpermute_b32 v13, v34, v9
	s_waitcnt lgkmcnt(0)
	v_add_f32_e32 v9, v9, v13
	ds_bpermute_b32 v13, v35, v9
	s_waitcnt lgkmcnt(0)
	v_add_f32_e32 v9, v9, v13
	ds_bpermute_b32 v13, v36, v9
	s_waitcnt lgkmcnt(0)
	v_add_f32_e32 v9, v9, v13
	v_fmamk_f32 v26, v9, 0xbb800000, v26
	v_fmamk_f32 v13, v9, 0xbb800000, v28
	v_fmac_f32_e32 v29, 0xbb800000, v9
	v_fmac_f32_e32 v27, 0xbb800000, v9
	v_mul_f32_e32 v9, v26, v26
	v_fmac_f32_e32 v9, v13, v13
	v_fmac_f32_e32 v9, v29, v29
	v_fmac_f32_e32 v9, v27, v27
	ds_bpermute_b32 v21, v1, v9
	s_waitcnt lgkmcnt(0)
	v_add_f32_e32 v9, v9, v21
	ds_bpermute_b32 v21, v32, v9
	s_waitcnt lgkmcnt(0)
	v_add_f32_e32 v9, v9, v21
	ds_bpermute_b32 v21, v33, v9
	s_waitcnt lgkmcnt(0)
	v_add_f32_e32 v9, v9, v21
	ds_bpermute_b32 v21, v34, v9
	s_waitcnt lgkmcnt(0)
	v_add_f32_e32 v9, v9, v21
	ds_bpermute_b32 v28, v35, v9
	v_ashrrev_i32_e32 v21, 31, v20
	v_lshlrev_b64 v[20:21], 9, v[20:21]
	v_lshl_add_u64 v[20:21], v[6:7], 0, v[20:21]
	s_waitcnt lgkmcnt(0)
	v_add_f32_e32 v9, v9, v28
	ds_bpermute_b32 v28, v36, v9
	s_waitcnt lgkmcnt(0)
	v_add_f32_e32 v9, v9, v28
	v_fmamk_f32 v9, v9, 0x3b800000, v38
	v_mul_f32_e32 v11, 0x4f800000, v9
	v_cmp_gt_f32_e32 vcc, s24, v9
	s_waitcnt vmcnt(1)
	v_mov_b32_e32 v31, v22
	v_mov_b32_e32 v41, v23
	v_cndmask_b32_e32 v9, v9, v11, vcc
	v_sqrt_f32_e32 v11, v9
	v_mov_b32_e32 v43, v24
	v_mov_b32_e32 v45, v25
	v_add_u32_e32 v22, -1, v11
	v_add_u32_e32 v23, 1, v11
	v_fma_f32 v24, -v22, v11, v9
	v_fma_f32 v28, -v23, v11, v9
	v_cmp_ge_f32_e64 s[0:1], 0, v24
	s_nop 1
	v_cndmask_b32_e64 v11, v11, v22, s[0:1]
	v_cmp_lt_f32_e64 s[0:1], 0, v28
	s_nop 1
	v_cndmask_b32_e64 v11, v11, v23, s[0:1]
	v_mul_f32_e32 v22, 0x37800000, v11
	v_cndmask_b32_e32 v11, v11, v22, vcc
	v_cmp_class_f32_e32 vcc, v9, v39
	s_nop 1
	v_cndmask_b32_e32 v9, v11, v9, vcc
	v_div_scale_f32 v11, s[0:1], v9, v9, 1.0
	v_rcp_f32_e32 v22, v11
	v_div_scale_f32 v23, vcc, 1.0, v9, 1.0
	v_fma_f32 v24, -v11, v22, 1.0
	v_fmac_f32_e32 v22, v24, v22
	v_mul_f32_e32 v24, v23, v22
	v_fma_f32 v25, -v11, v24, v23
	v_fmac_f32_e32 v24, v25, v22
	v_fma_f32 v11, -v11, v24, v23
	v_div_fmas_f32 v11, v11, v22, v24
	v_div_fixup_f32 v11, v11, v9, 1.0
	v_mul_f32_e32 v9, v13, v11
	v_pk_mul_f32 v[22:23], v[30:31], v[8:9]
	v_mul_f32_e32 v9, v26, v11
	v_mul_f32_e32 v13, v22, v23
	v_pk_mul_f32 v[22:23], v[40:41], v[8:9]
	v_mul_f32_e32 v9, v29, v11
	v_mul_f32_e32 v24, v22, v23
	v_pk_mul_f32 v[22:23], v[42:43], v[8:9]
	v_mul_f32_e32 v9, v27, v11
	v_mul_f32_e32 v11, v22, v23
	v_pk_mul_f32 v[22:23], v[44:45], v[8:9]
	v_cvt_pk_bf16_f32 v24, v13, v24
	s_nop 0
	v_mul_f32_e32 v9, v22, v23
	v_cvt_pk_bf16_f32 v25, v11, v9
	global_store_dwordx2 v[20:21], v[24:25], off
	s_or_b64 exec, exec, s[14:15]
	v_cmp_gt_i32_e32 vcc, s18, v10
	s_and_saveexec_b64 s[14:15], vcc
	s_cbranch_execz .LBB0_523
; __device__ __forceinline__ unsigned pk2(float lo, float hi) { unsigned r; asm("v_cvt_pk_bf16_f32 %0, %1, %2" : "=v"(r) : "v"(lo), "v"(hi)); return r; }
; __device__ __forceinline__ void phase_mlnorm(const Params& p) {
;     ...
;         for (int u = 0; u < 4; ++u) { const int wi = w0 + u * NW; if (wi >= T * 4) continue; const size_t off = (size_t)wi * 256 + lane * 4;
;             float v[4] = {bflo(a[u].x) + bflo(b[u].x), bfhi(a[u].x) + bfhi(b[u].x), bflo(a[u].y) + bflo(b[u].y), bfhi(a[u].y) + bfhi(b[u].y)};
;             const float mu = wave_sum((v[0] + v[1]) + (v[2] + v[3])) * (1.0f / 256.0f);
;             float q = 0.f;
; #pragma unroll
;             for (int i = 0; i < 4; ++i) { v[i] -= mu; q += v[i] * v[i]; }
;             const float rstd = 1.0f / sqrtf(wave_sum(q) * (1.0f / 256.0f) + LN_EPS);
;             const f32x4 nwv = *(const f32x4*)(nw + (wi & 3) * 256 + lane * 4);
;             const float og[4] = {(float)(o[u] & 0xffu) * (1.0f / 255.0f), (float)((o[u] >> 8) & 0xffu) * (1.0f / 255.0f), (float)((o[u] >> 16) & 0xffu) * (1.0f / 255.0f), (float)(o[u] >> 24) * (1.0f / 255.0f)};
;             u32x2 wv; wv.x = pk2(v[0] * rstd * nwv[0] * og[0], v[1] * rstd * nwv[1] * og[1]); wv.y = pk2(v[2] * rstd * nwv[2] * og[2], v[3] * rstd * nwv[3] * og[3]);
;             *(u32x2*)(yml + off) = wv; }
.LBB0_529:
	s_waitcnt vmcnt(1)
	v_lshlrev_b32_e32 v20, 16, v18
	v_lshlrev_b32_e32 v22, 16, v16
	v_and_b32_e32 v18, 0xffff0000, v18
	v_and_b32_e32 v16, 0xffff0000, v16
	v_lshlrev_b32_e32 v21, 16, v19
	v_lshlrev_b32_e32 v23, 16, v17
	v_and_b32_e32 v19, 0xffff0000, v19
	v_and_b32_e32 v17, 0xffff0000, v17
	v_pk_add_f32 v[20:21], v[22:23], v[20:21]
	v_pk_add_f32 v[18:19], v[16:17], v[18:19]
	v_cvt_f32_ubyte0_e32 v22, v2
	v_pk_add_f32 v[16:17], v[20:21], v[18:19]
	v_cvt_f32_ubyte1_e32 v24, v2
	v_add_f32_e32 v9, v16, v17
	ds_bpermute_b32 v11, v1, v9
	v_mov_b32_e32 v14, v64
	v_mov_b32_e32 v15, v65
	v_mov_b32_e32 v16, v66
	v_mov_b32_e32 v17, v67
	v_cvt_f32_ubyte2_e32 v26, v2
	v_cvt_f32_ubyte3_e32 v28, v2
	s_waitcnt lgkmcnt(0)
	v_add_f32_e32 v9, v9, v11
	ds_bpermute_b32 v11, v32, v9
	s_waitcnt lgkmcnt(0)
	v_add_f32_e32 v9, v9, v11
	ds_bpermute_b32 v11, v33, v9
	s_waitcnt lgkmcnt(0)
	v_add_f32_e32 v9, v9, v11
	ds_bpermute_b32 v11, v34, v9
	s_waitcnt lgkmcnt(0)
	v_add_f32_e32 v9, v9, v11
	ds_bpermute_b32 v11, v35, v9
	s_waitcnt lgkmcnt(0)
	v_add_f32_e32 v9, v9, v11
	ds_bpermute_b32 v11, v36, v9
	s_waitcnt lgkmcnt(0)
	v_add_f32_e32 v9, v9, v11
	v_fmamk_f32 v18, v9, 0xbb800000, v18
	v_fmamk_f32 v13, v9, 0xbb800000, v20
	v_fmac_f32_e32 v21, 0xbb800000, v9
	v_fmac_f32_e32 v19, 0xbb800000, v9
	v_mul_f32_e32 v9, v18, v18
	v_fmac_f32_e32 v9, v13, v13
	v_fmac_f32_e32 v9, v21, v21
	v_fmac_f32_e32 v9, v19, v19
	ds_bpermute_b32 v11, v1, v9
	s_waitcnt lgkmcnt(0)
	v_add_f32_e32 v9, v9, v11
	ds_bpermute_b32 v11, v32, v9
	s_waitcnt lgkmcnt(0)
	v_add_f32_e32 v9, v9, v11
	ds_bpermute_b32 v11, v33, v9
	s_waitcnt lgkmcnt(0)
	v_add_f32_e32 v9, v9, v11
	ds_bpermute_b32 v11, v34, v9
	s_waitcnt lgkmcnt(0)
	v_add_f32_e32 v9, v9, v11
	ds_bpermute_b32 v20, v35, v9
	v_ashrrev_i32_e32 v11, 31, v10
	v_lshlrev_b64 v[10:11], 9, v[10:11]
	v_lshl_add_u64 v[10:11], v[6:7], 0, v[10:11]
	s_waitcnt lgkmcnt(0)
	v_add_f32_e32 v9, v9, v20
	ds_bpermute_b32 v20, v36, v9
	s_waitcnt lgkmcnt(0)
	v_add_f32_e32 v2, v9, v20
	v_fmamk_f32 v2, v2, 0x3b800000, v38
	v_mul_f32_e32 v9, 0x4f800000, v2
	v_cmp_gt_f32_e32 vcc, s24, v2
	s_waitcnt vmcnt(1)
	v_mov_b32_e32 v23, v14
	v_mov_b32_e32 v25, v15
	v_cndmask_b32_e32 v2, v2, v9, vcc
	v_sqrt_f32_e32 v9, v2
	v_mov_b32_e32 v27, v16
	v_mov_b32_e32 v29, v17
	v_add_u32_e32 v14, -1, v9
	v_add_u32_e32 v15, 1, v9
	v_fma_f32 v16, -v14, v9, v2
	v_fma_f32 v20, -v15, v9, v2
	v_cmp_ge_f32_e64 s[0:1], 0, v16
	s_nop 1
	v_cndmask_b32_e64 v9, v9, v14, s[0:1]
	v_cmp_lt_f32_e64 s[0:1], 0, v20
	s_nop 1
	v_cndmask_b32_e64 v9, v9, v15, s[0:1]
	v_mul_f32_e32 v14, 0x37800000, v9
	v_cndmask_b32_e32 v9, v9, v14, vcc
	v_cmp_class_f32_e32 vcc, v2, v39
	s_nop 1
	v_cndmask_b32_e32 v2, v9, v2, vcc
	v_div_scale_f32 v9, s[0:1], v2, v2, 1.0
	v_rcp_f32_e32 v14, v9
	v_div_scale_f32 v15, vcc, 1.0, v2, 1.0
	v_fma_f32 v16, -v9, v14, 1.0
	v_fmac_f32_e32 v14, v16, v14
	v_mul_f32_e32 v16, v15, v14
	v_fma_f32 v17, -v9, v16, v15
	v_fmac_f32_e32 v16, v17, v14
	v_fma_f32 v9, -v9, v16, v15
	v_div_fmas_f32 v9, v9, v14, v16
	v_div_fixup_f32 v2, v9, v2, 1.0
	v_mul_f32_e32 v9, v13, v2
	v_pk_mul_f32 v[14:15], v[22:23], v[8:9]
	v_mul_f32_e32 v9, v18, v2
	v_mul_f32_e32 v13, v14, v15
	v_pk_mul_f32 v[14:15], v[24:25], v[8:9]
	v_mul_f32_e32 v9, v21, v2
	v_mul_f32_e32 v16, v14, v15
	v_pk_mul_f32 v[14:15], v[26:27], v[8:9]
	v_mul_f32_e32 v9, v19, v2
	v_mul_f32_e32 v2, v14, v15
	v_pk_mul_f32 v[14:15], v[28:29], v[8:9]
	v_cvt_pk_bf16_f32 v16, v13, v16
	s_nop 0
	v_mul_f32_e32 v9, v14, v15
	v_cvt_pk_bf16_f32 v17, v2, v9
	global_store_dwordx2 v[10:11], v[16:17], off
	s_branch .LBB0_523
